# phase_fix: compacted item list (only first/sample/batch-final groups), one item per thread
# speedup vs baseline: 1.0072x; 1.0072x over previous
.LBB0_383:
	s_and_b64 vcc, exec, s[2:3]
	s_cbranch_vccz .LBB0_400
	s_mov_b64 s[2:3], s[36:37]
	v_readlane_b32 s0, v253, 0
	s_waitcnt vmcnt(0)
	v_mov_b32_e32 v0, v224
	s_mov_b32 s1, 0x16dc0
	v_lshl_add_u32 v112, s0, 9, v0
	s_mov_b32 s0, s54
	v_cmp_gt_i32_e32 vcc, s1, v112
	s_and_saveexec_b64 s[8:9], vcc
	s_cbranch_execz .LBB0_399
	s_mov_b32 s4, 0x2e8ba2e9
	v_mul_hi_i32 v124, v112, s4
	v_ashrrev_i32_e32 v124, 6, v124
	v_mul_i32_i24_e32 v125, 0x160, v124
	v_sub_u32_e32 v125, v112, v125
	v_lshlrev_b32_e32 v126, 2, v124
	v_add_u32_e32 v127, 0x2fe, v124
	v_cmp_lt_u32_e32 vcc, 0x101, v124
	s_nop 1
	v_cndmask_b32_e32 v126, v126, v127, vcc
	v_mov_b32_e32 v127, 0x1ff
	v_cmp_eq_u32_e32 vcc, 0x100, v124
	s_nop 1
	v_cndmask_b32_e32 v126, v126, v127, vcc
	v_mov_b32_e32 v127, 0x3ff
	v_cmp_eq_u32_e32 vcc, 0x101, v124
	s_nop 1
	v_cndmask_b32_e32 v126, v126, v127, vcc
	v_mul_i32_i24_e32 v126, 0x160, v126
	v_add_u32_e32 v112, v126, v125
	s_load_dwordx2 s[4:5], s[2:3], 0xa8
	s_load_dwordx4 s[20:23], s[2:3], 0x88
	s_lshl_b32 s6, s0, 9
	s_waitcnt vmcnt(3)
	v_lshlrev_b32_e32 v118, 3, v112
	s_mov_b64 s[52:53], 0
	s_waitcnt lgkmcnt(0)
	s_add_u32 s10, s4, 0x6000000
	s_addc_u32 s11, s5, 0
	s_add_u32 s14, s4, 0x8d00000
	s_addc_u32 s15, s5, 0
	v_readlane_b32 s5, v254, 21
	s_and_b32 s1, 0xffff, s5
	s_mul_i32 s4, s1, 0x10800
	s_add_u32 s18, s20, s4
	s_mulk_i32 s1, 0x5800
	s_addc_u32 s19, s21, 0
	s_add_u32 s20, s22, s1
	s_addc_u32 s21, s23, 0
	s_add_u32 s34, s18, 0x5800
	s_addc_u32 s35, s19, 0
	s_add_u32 s42, s18, 0xb000
	s_addc_u32 s43, s19, 0
	s_add_u32 s44, s18, 0x2c00
	s_addc_u32 s45, s19, 0
	s_add_u32 s46, s18, 0x8400
	s_addc_u32 s47, s19, 0
	s_add_u32 s48, s18, 0xdc00
	s_addc_u32 s49, s19, 0
	s_add_u32 s50, s20, 0x2c00
	s_addc_u32 s51, s21, 0
	s_lshl_b32 s7, s5, 4
	s_lshl_b32 s12, s5, 2
	s_lshl_b32 s13, s0, 12
	s_branch .LBB0_388

.LBB0_387:
	s_or_b64 exec, exec, s[0:1]
	s_mov_b64 exec, s[74:75]
	v_add_u32_e32 v112, s6, v112
	s_mov_b32 s0, -1
	v_cmp_lt_i32_e32 vcc, s0, v112
	s_or_b64 s[52:53], vcc, s[52:53]
	v_add_u32_e32 v118, s13, v118
	s_andn2_b64 exec, exec, s[52:53]
	s_cbranch_execz .LBB0_399
